# v027 plus nt on attention Q loads
# speedup vs baseline: 1.0103x; 1.0103x over previous
; __device__ __forceinline__ void attnB_wave(LAS unsigned char* st, const bf16* QKV, bf16* O, float* sso, int b, int h, int qi, int lane) {
;     const int ql = lane & 31, hi = lane >> 5, q0 = 32 * qi;
;     const size_t tb = (size_t)b * SEQ;
;     const AtdAddr A = atd_addr(QKV + tb * 3072 + 1536 + h * 64, QKV + tb * 3072 + 2048 + 512 + h * 64, lane);
;     const bf16* Qp = QKV + (tb + q0 + ql) * 3072 + 1024 + h * 64 + hi * 8;
;     bf16x8 qf[4];
; #pragma unroll
;     for (int d0 = 0; d0 < 4; ++d0) qf[d0] = *(const bf16x8*)(Qp + d0 * 16);
;     const int n = qi + 1;
;     ATD_DMA(A, st, qi, 0);
;     if (n > 1) ATD_DMA(A, st, qi - 1, 1);
; __device__ __forceinline__ void phase_attn(const Ctx& C, const float* relb  , int layer) {
;     ...
;               if (lane == 0) idx = __hip_atomic_fetch_add(qb_, 1u, __ATOMIC_RELAXED, __HIP_MEMORY_SCOPE_AGENT);
;               idx = (unsigned)__builtin_amdgcn_readfirstlane((int)idx);
;               if (idx >= (unsigned)per_q) break;
;               const int bh = x * 8 + (int)(idx >> 7), qi = 127 - (int)(idx & 127);
;               attnB_wave(st, QKV, O, sso, bh >> 3, bh & 7, qi, lane);
.LBB0_267:
	s_or_b64 exec, exec, s[12:13]
	s_waitcnt vmcnt(0) lgkmcnt(0)
	v_readfirstlane_b32 s10, v0
	s_cmpk_gt_u32 s10, 0x3ff
	s_mov_b64 s[12:13], -1
	s_cbranch_scc1 .LBB0_264
	s_and_b32 s3, s10, 0x7f
	s_lshr_b32 s10, s10, 1
	s_and_b32 s10, s10, 0x1c0
	s_lshl_b32 s12, s10, 1
	s_mov_b32 s13, s11
	s_xor_b32 s81, s3, 0x7f
	v_lshl_add_u64 v[0:1], v[134:135], 0, s[12:13]
	s_lshl_b32 s80, s81, 5
	v_lshl_add_u64 v[102:103], v[118:119], 1, v[0:1]
	v_lshl_add_u64 v[104:105], v[120:121], 1, v[0:1]
	v_lshl_add_u64 v[0:1], v[98:99], 0, s[12:13]
	v_lshl_add_u64 v[106:107], v[122:123], 1, v[0:1]
	v_lshl_add_u64 v[108:109], v[124:125], 1, v[0:1]
	v_or_b32_e32 v80, s80, v136
	v_mov_b64_e32 v[0:1], s[14:15]
	v_mad_u64_u32 v[0:1], s[78:79], v80, s0, v[0:1]
	v_lshl_add_u64 v[0:1], v[0:1], 0, s[12:13]
	v_lshl_add_u64 v[0:1], v[128:129], 1, v[0:1]
	s_mul_i32 s10, s81, 0x30000
	flat_load_dwordx4 v[64:67], v[0:1] offset:2048 nt
	flat_load_dwordx4 v[68:71], v[0:1] offset:2080 nt
	flat_load_dwordx4 v[72:75], v[0:1] offset:2112 nt
	flat_load_dwordx4 v[76:79], v[0:1] offset:2144 nt
	v_lshl_add_u64 v[0:1], v[102:103], 0, s[10:11]
	s_mov_b32 m0, s33
	v_lshl_add_u64 v[2:3], v[0:1], 0, s[22:23]
	global_load_lds_dwordx4 v[2:3], off
	v_lshl_add_u64 v[2:3], v[104:105], 0, s[10:11]
	s_add_i32 s13, s33, 0x400
	v_lshl_add_u64 v[4:5], v[2:3], 0, s[74:75]
	s_mov_b32 m0, s13
	s_add_i32 s82, s33, 0x800
	global_load_lds_dwordx4 v[4:5], off
	v_lshl_add_u64 v[0:1], v[0:1], 0, s[76:77]
	s_mov_b32 m0, s82
	s_add_i32 s83, s33, 0xc00
	global_load_lds_dwordx4 v[0:1], off
	v_lshl_add_u64 v[0:1], v[2:3], 0, s[24:25]
	s_mov_b32 m0, s83
	s_add_i32 s86, s33, 0x1000
	global_load_lds_dwordx4 v[0:1], off
	v_lshl_add_u64 v[0:1], v[106:107], 0, s[10:11]
	s_mov_b32 m0, s86
	v_lshl_add_u64 v[2:3], v[108:109], 0, s[10:11]
	s_add_i32 s87, s33, 0x1400
	global_load_lds_dwordx4 v[0:1], off
	v_lshl_add_u64 v[4:5], v[2:3], 0, s[26:27]
	s_mov_b32 m0, s87
	s_add_i32 s88, s33, 0x1800
	global_load_lds_dwordx4 v[4:5], off
	v_lshl_add_u64 v[0:1], v[0:1], 0, s[28:29]
	s_mov_b32 m0, s88
	s_add_i32 s89, s33, 0x1c00
	global_load_lds_dwordx4 v[0:1], off
	v_lshl_add_u64 v[0:1], v[2:3], 0, s[30:31]
	s_mov_b32 m0, s89
	s_cmpk_eq_i32 s3, 0x7f
	global_load_lds_dwordx4 v[0:1], off
	s_cselect_b64 s[78:79], -1, 0
	s_cmpk_lg_i32 s3, 0x7f
	s_cselect_b64 s[84:85], -1, 0
	s_and_b64 vcc, exec, s[78:79]
	s_cbranch_vccnz .LBB0_270
	s_mul_i32 s10, s81, 0x18000
	s_add_i32 s10, s10, 0xfffe8000
	s_lshl_b64 s[90:91], s[10:11], 1
	v_lshl_add_u64 v[0:1], v[102:103], 0, s[90:91]
	v_lshl_add_u64 v[2:3], v[0:1], 0, s[22:23]
	s_add_i32 m0, s33, 0x2000
	v_readlane_b32 s10, v255, 32
	global_load_lds_dwordx4 v[2:3], off
	v_lshl_add_u64 v[2:3], v[104:105], 0, s[90:91]
	v_lshl_add_u64 v[4:5], v[2:3], 0, s[74:75]
	s_mov_b32 m0, s10
	v_readlane_b32 s10, v255, 33
	global_load_lds_dwordx4 v[4:5], off
	v_lshl_add_u64 v[0:1], v[0:1], 0, s[76:77]
	s_mov_b32 m0, s10
	v_readlane_b32 s10, v255, 34
	global_load_lds_dwordx4 v[0:1], off
	v_lshl_add_u64 v[0:1], v[2:3], 0, s[24:25]
	s_mov_b32 m0, s10
	v_readlane_b32 s10, v255, 35
	global_load_lds_dwordx4 v[0:1], off
	v_lshl_add_u64 v[0:1], v[106:107], 0, s[90:91]
	s_mov_b32 m0, s10
	v_lshl_add_u64 v[2:3], v[108:109], 0, s[90:91]
	v_readlane_b32 s10, v255, 36
	global_load_lds_dwordx4 v[0:1], off
	v_lshl_add_u64 v[4:5], v[2:3], 0, s[26:27]
	s_mov_b32 m0, s10
	v_readlane_b32 s10, v255, 37
	global_load_lds_dwordx4 v[4:5], off
	v_lshl_add_u64 v[0:1], v[0:1], 0, s[28:29]
	s_mov_b32 m0, s10
	s_mov_b64 s[90:91], 0x1000
	global_load_lds_dwordx4 v[0:1], off
	v_lshl_add_u64 v[0:1], v[2:3], 0, s[30:31]
	s_mov_b32 m0, s8
	s_nop 0
	global_load_lds_dwordx4 v[0:1], off

; #define ATD_KFRAGS(kf_, A_, st_, s_) do { LAS unsigned char* b_ = (st_) + (s_) * ATD_STAGE; \
;         _Pragma("unroll") for (int d0 = 0; d0 < 4; ++d0) kf_[d0] = *(const LAS bf16x8*)(b_ + (A_).koff[d0]); \
;         asm volatile("s_waitcnt lgkmcnt(0)" ::: "memory"); } while (0)
; __device__ __forceinline__ void attnA_wave(LAS unsigned char* st, const LAS float* tb2, const bf16* QKV, bf16* O, float* sso, int b, int h, int qblk, int lane) {
;     const int ql = lane & 31, hi = lane >> 5, q0 = 32 * qblk, c = qblk >> 1;
;     const size_t tb = (size_t)b * SEQ;
;     const AtdAddr A = atd_addr(QKV + tb * 3072 + 512 + h * 64, QKV + tb * 3072 + 2048 + h * 64, lane);
;     const bf16* Qp = QKV + (tb + q0 + ql) * 3072 + h * 64 + hi * 8;
;     bf16x8 qf[4];
; #pragma unroll
;     for (int d0 = 0; d0 < 4; ++d0) qf[d0] = *(const bf16x8*)(Qp + d0 * 16);
;     AState S;
; #pragma unroll
;     for (int r = 0; r < 16; ++r) { S.o0[r] = 0.f; S.o1[r] = 0.f; }
;     S.mrun = -1e30f; S.l = 0.f;
;     const float bfar = tb2[256];
;     const int t0 = (c > 8 ? c - 8 : 0) * 2, n = c * 2 + 2 - t0;
;     ATD_DMA(A, st, t0, 0);
;     ATD_DMA(A, st, t0 + 1, 1);
;     asm volatile("s_waitcnt vmcnt(0)" ::: "memory");
;     bf16x8 kf[4], vfc[4]; f32x16 sc;
;     ATD_KFRAGS(kf, A, st, 0); ATD_VFRAGS(vfc, A, st, 0);
;     if (n > 2) ATD_DMA(A, st, t0 + 2, 0);
; __device__ __forceinline__ void phase_attn(const Ctx& C, const float* relb  , int layer) {
;     ...
;               if (lane == 0) idx = __hip_atomic_fetch_add(qa_, 1u, __ATOMIC_RELAXED, __HIP_MEMORY_SCOPE_AGENT);
;               idx = (unsigned)__builtin_amdgcn_readfirstlane((int)idx);
;               if (idx >= (unsigned)per_q) break;
;               const int bh = x * 8 + (int)(idx >> 7), qb = 127 - (int)(idx & 127);
;               attnA_wave(st, tbl + (bh & 7) * 257, QKV, O, sso, bh >> 3, bh & 7, qb, lane);
.LBB0_304:
	s_or_b64 exec, exec, s[12:13]
	s_waitcnt vmcnt(0) lgkmcnt(0)
	v_readfirstlane_b32 s3, v0
	s_cmpk_gt_u32 s3, 0x3ff
	s_mov_b64 s[12:13], -1
	s_cbranch_scc1 .LBB0_301
	s_lshr_b32 s80, s3, 7
	s_and_b32 s10, s3, 0xffffff80
	s_andn2_b32 s78, 0x7f, s3
	s_mul_i32 s2, s80, 0x404
	v_lshl_add_u64 v[0:1], v[134:135], 0, s[10:11]
	s_add_i32 s81, s2, 0
	s_lshl_b32 s2, s78, 5
	v_lshl_add_u64 v[142:143], v[118:119], 1, v[0:1]
	v_lshl_add_u64 v[144:145], v[120:121], 1, v[0:1]
	v_lshl_add_u64 v[0:1], v[138:139], 0, s[10:11]
	v_lshl_add_u64 v[146:147], v[122:123], 1, v[0:1]
	v_lshl_add_u64 v[148:149], v[124:125], 1, v[0:1]
	v_or_b32_e32 v156, s2, v136
	v_mov_b64_e32 v[0:1], s[14:15]
	v_mad_u64_u32 v[0:1], s[12:13], v156, s0, v[0:1]
	s_andn2_b32 s3, 0x7e, s3
	s_add_i32 s81, s81, 0x20400
	v_lshl_add_u64 v[0:1], v[0:1], 0, s[10:11]
	s_add_i32 s10, s3, -16
	s_cmp_gt_u32 s78, 17
	s_cselect_b32 s10, s10, 0
	s_mul_i32 s12, s10, 0x18000
	v_lshl_add_u64 v[0:1], v[128:129], 1, v[0:1]
	s_ashr_i32 s13, s12, 31
	flat_load_dwordx4 v[82:85], v[0:1] nt
	flat_load_dwordx4 v[86:89], v[0:1] offset:32 nt
	flat_load_dwordx4 v[90:93], v[0:1] offset:64 nt
	flat_load_dwordx4 v[94:97], v[0:1] offset:96 nt
	v_mov_b32_e32 v0, s81
	s_lshl_b64 s[12:13], s[12:13], 1
	ds_read_b32 v157, v0 offset:1024
	v_lshl_add_u64 v[0:1], v[142:143], 0, s[12:13]
	s_mov_b32 m0, s33
	v_lshl_add_u64 v[2:3], v[0:1], 0, s[34:35]
	s_sub_i32 s82, s3, s10
	global_load_lds_dwordx4 v[2:3], off
	v_lshl_add_u64 v[2:3], v[144:145], 0, s[12:13]
	s_add_i32 s3, s33, 0x400
	v_lshl_add_u64 v[4:5], v[2:3], 0, s[96:97]
	s_mov_b32 m0, s3
	s_add_i32 s78, s33, 0x800
	global_load_lds_dwordx4 v[4:5], off
	v_lshl_add_u64 v[0:1], v[0:1], 0, s[72:73]
	s_mov_b32 m0, s78
	s_add_i32 s79, s33, 0xc00
	global_load_lds_dwordx4 v[0:1], off
	v_lshl_add_u64 v[0:1], v[2:3], 0, s[6:7]
	s_mov_b32 m0, s79
	s_add_i32 s83, s33, 0x1000
	global_load_lds_dwordx4 v[0:1], off
	v_lshl_add_u64 v[0:1], v[146:147], 0, s[12:13]
	s_mov_b32 m0, s83
	v_lshl_add_u64 v[2:3], v[148:149], 0, s[12:13]
	s_add_i32 s84, s33, 0x1400
	s_add_i32 s82, s82, 2
	global_load_lds_dwordx4 v[0:1], off
	v_lshl_add_u64 v[4:5], v[2:3], 0, s[26:27]
	s_mov_b32 m0, s84
	s_add_i32 s85, s33, 0x1800
	s_add_i32 s86, s33, 0x1c00
	global_load_lds_dwordx4 v[4:5], off
	v_lshl_add_u64 v[0:1], v[0:1], 0, s[28:29]
	s_mov_b32 m0, s85
	s_add_u32 s88, s12, 0x30000
	v_lshl_add_u64 v[18:19], v[142:143], 0, s[34:35]
	v_lshl_add_u64 v[16:17], v[144:145], 0, s[34:35]
	global_load_lds_dwordx4 v[0:1], off
	v_lshl_add_u64 v[0:1], v[2:3], 0, s[30:31]
	s_mov_b32 m0, s86
	s_addc_u32 s89, s13, 0
	global_load_lds_dwordx4 v[0:1], off
	v_lshl_add_u64 v[0:1], v[18:19], 0, s[88:89]
	s_add_i32 m0, s33, 0x2000
	v_lshl_add_u64 v[2:3], v[16:17], 0, s[88:89]
	v_readlane_b32 s87, v255, 32
	global_load_lds_dwordx4 v[0:1], off
	v_lshl_add_u64 v[4:5], v[2:3], 0, s[26:27]
	s_mov_b32 m0, s87
	v_readlane_b32 s87, v255, 33
	global_load_lds_dwordx4 v[4:5], off
	v_lshl_add_u64 v[0:1], v[0:1], 0, s[28:29]
	s_mov_b32 m0, s87
	v_readlane_b32 s87, v255, 34
	global_load_lds_dwordx4 v[0:1], off
	v_lshl_add_u64 v[0:1], v[2:3], 0, s[30:31]
	s_mov_b32 m0, s87
	v_readlane_b32 s87, v255, 35
	global_load_lds_dwordx4 v[0:1], off
	v_lshl_add_u64 v[0:1], v[146:147], 0, s[88:89]
	s_mov_b32 m0, s87
	v_lshl_add_u64 v[2:3], v[148:149], 0, s[88:89]
	v_readlane_b32 s87, v255, 36
	global_load_lds_dwordx4 v[0:1], off
	v_lshl_add_u64 v[4:5], v[2:3], 0, s[26:27]
	s_mov_b32 m0, s87
	v_readlane_b32 s87, v255, 37
	global_load_lds_dwordx4 v[4:5], off
	v_lshl_add_u64 v[0:1], v[0:1], 0, s[28:29]
	s_mov_b32 m0, s87
	v_add_u32_e32 v20, s33, v152
	global_load_lds_dwordx4 v[0:1], off
	v_lshl_add_u64 v[0:1], v[2:3], 0, s[30:31]
	s_mov_b32 m0, s8
	v_add_u32_e32 v21, s33, v153
	global_load_lds_dwordx4 v[0:1], off
	s_waitcnt vmcnt(0)
	v_add_u32_e32 v0, s33, v115
	v_add_u32_e32 v1, s33, v137
	ds_read_b128 v[8:11], v0
	ds_read_b128 v[4:7], v1
	v_add_u32_e32 v0, s33, v150
	v_add_u32_e32 v1, s33, v151
	ds_read_b128 v[12:15], v0
	ds_read_b128 v[0:3], v1
	s_waitcnt lgkmcnt(0)
	s_waitcnt vmcnt(0)
	ds_read_b64_tr_b16 v[98:99], v20 offset:4096
	ds_read_b64_tr_b16 v[100:101], v21 offset:4096
	ds_read_b64_tr_b16 v[104:105], v21 offset:6144
	ds_read_b64_tr_b16 v[102:103], v20 offset:6144
	v_add_u32_e32 v20, s33, v154
	v_add_u32_e32 v21, s33, v155
	ds_read_b64_tr_b16 v[106:107], v20 offset:4096
	ds_read_b64_tr_b16 v[108:109], v21 offset:4096
	ds_read_b64_tr_b16 v[112:113], v21 offset:6144
	ds_read_b64_tr_b16 v[110:111], v20 offset:6144
	s_waitcnt lgkmcnt(0)
	s_cmp_lt_i32 s82, 3
	s_cbranch_scc1 .LBB0_307
	s_add_u32 s12, s12, 0x60000
	s_addc_u32 s13, s13, 0
	s_mov_b32 m0, s33
	v_lshl_add_u64 v[18:19], v[18:19], 0, s[12:13]
	v_lshl_add_u64 v[16:17], v[16:17], 0, s[12:13]
	global_load_lds_dwordx4 v[18:19], off
	v_lshl_add_u64 v[20:21], v[16:17], 0, s[26:27]
	s_mov_b32 m0, s3
	v_lshl_add_u64 v[18:19], v[18:19], 0, s[28:29]
	global_load_lds_dwordx4 v[20:21], off
	s_mov_b32 m0, s78
	v_lshl_add_u64 v[16:17], v[16:17], 0, s[30:31]
	global_load_lds_dwordx4 v[18:19], off
	s_mov_b32 m0, s79
	v_lshl_add_u64 v[18:19], v[148:149], 0, s[12:13]
	global_load_lds_dwordx4 v[16:17], off
	v_lshl_add_u64 v[16:17], v[146:147], 0, s[12:13]
	s_mov_b32 m0, s83
	v_lshl_add_u64 v[20:21], v[18:19], 0, s[26:27]
	global_load_lds_dwordx4 v[16:17], off
	s_mov_b32 m0, s84
	v_lshl_add_u64 v[16:17], v[16:17], 0, s[28:29]
	global_load_lds_dwordx4 v[20:21], off
	s_mov_b32 m0, s85
	s_nop 0
	global_load_lds_dwordx4 v[16:17], off
	v_lshl_add_u64 v[16:17], v[18:19], 0, s[30:31]
	s_mov_b32 m0, s86
	s_nop 0
	global_load_lds_dwordx4 v[16:17], off
